# P4 epilogue: straight-line fast path for prompt units of column panels 6..13 (bf16 PB store only), other unit kinds keep the original branch tree
# baseline (speedup 1.0000x reference)
; #define EM_PK8(a, b) ((u32x4){cvt_pk_bf16((a)[0], (a)[1]), cvt_pk_bf16((a)[2], (a)[3]), cvt_pk_bf16((b)[0], (b)[1]), cvt_pk_bf16((b)[2], (b)[3])})
;     __device__ __forceinline__ void operator()(const f32x4 (&acc)[2][2][4][2], const Unit& u, int wr, int wc, int fr, int fq) const {
;         const int pn = u.pn; const bool samp = u.pm * BM >= mp;
;         const int col0 = pn * BM + wc * 32 + 8 * fq;
;     ...
; #pragma unroll
;         for (int ai = 0; ai < 2; ++ai)
; #pragma unroll
;             for (int m = 0; m < 4; ++m) { const int row = u.pm * BM + ai * HALF + wr * 64 + m * 16 + fr;
; #pragma unroll
;                 for (int bj = 0; bj < 2; ++bj) { const int col = col0 + bj * HALF; const f32x4 v0 = acc[ai][bj][m][0], v1 = acc[ai][bj][m][1];
;                     if (samp || pn == 14) { float* pp = P + (size_t)row * 3840 + col; *(f32x4*)pp = v0; *(f32x4*)(pp + 4) = v1; }
;                     else if (pn >= 6) *(u32x4*)(PB + (size_t)row * 2048 + (col - 1536)) = EM_PK8(v0, v1);
;                     if (pn < 2) { if (!samp) { const f32x4 q0 = v0 * c2, q1 = v1 * c2; *(u32x4*)(Qb + (size_t)row * 512 + col) = EM_PK8(q0, q1); } }
;                     else if (pn < 4) { const int c = col - 512; float* ko = (samp ? out + o_ks + (size_t)(row - mp) * 512 : out + o_kp + (size_t)row * 512) + c; *(f32x4*)ko = v0; *(f32x4*)(ko + 4) = v1;
;                         if (!samp) *(u32x4*)(Kb + (size_t)row * 512 + c) = EM_PK8(v0, v1); }
;                     else if (pn < 6) { const int c = col - 1024; float* vo = (samp ? out + o_vs + (size_t)(row - mp) * 512 : out + o_vp + (size_t)row * 512) + c; *(f32x4*)vo = v0; *(f32x4*)(vo + 4) = v1;
;                         if (!samp) *(u32x4*)(Vb + (size_t)row * 512 + c) = EM_PK8(v0, v1); }
;                     else if (pn < 12) { const int c = col - 1536;
;                         if (!samp) { const int b = row / seq, t = row - b * seq; if (t >= seq - 3) { float* so = out + o_scp + ((size_t)b * 3 + (t - (seq - 3))) * 1536 + c; *(f32x4*)so = v0; *(f32x4*)(so + 4) = v1; } }
;                         else { const int sr = row - mp, b = sr / ds, t = sr - b * ds; if (t >= 1) { float* so = out + o_scs + ((size_t)b * 3 + (t - 1)) * 1536 + c; *(f32x4*)so = v0; *(f32x4*)(so + 4) = v1; } } }
.LBB0_337:
	s_cmp_lt_i32 s6, 64
	s_cbranch_scc0 .Lp4epi_generic
	s_sub_u32 s98, s8, 6
	s_cmp_lt_u32 s98, 8
	s_cbranch_scc0 .Lp4epi_generic
	s_cmp_gt_u32 s8, 11
	s_cbranch_scc1 .Lp4epi_fast
	s_and_b32 s98, s6, 7
	s_cmp_eq_u32 s98, 7
	s_cbranch_scc1 .Lp4epi_generic
.Lp4epi_fast:
	v_lshl_add_u32 v254, s6, 8, v1
	v_lshl_or_b32 v255, s8, 8, v163
	v_lshlrev_b32_e32 v254, 12, v254
	v_lshl_add_u32 v254, v255, 1, v254
	v_add_u32_e32 v254, 0xfffff400, v254
	v_cvt_pk_bf16_f32 v246, v126, v127
	v_cvt_pk_bf16_f32 v247, v128, v129
	v_cvt_pk_bf16_f32 v248, v122, v123
	v_cvt_pk_bf16_f32 v249, v124, v125
	global_store_dwordx4 v254, v[246:249], s[64:65]
	v_cvt_pk_bf16_f32 v250, v118, v119
	v_cvt_pk_bf16_f32 v251, v120, v121
	v_cvt_pk_bf16_f32 v252, v114, v115
	v_cvt_pk_bf16_f32 v253, v116, v117
	global_store_dwordx4 v254, v[250:253], s[64:65] offset:256
	v_add_u32_e32 v255, 0x10000, v254
	v_cvt_pk_bf16_f32 v246, v110, v111
	v_cvt_pk_bf16_f32 v247, v112, v113
	v_cvt_pk_bf16_f32 v248, v106, v107
	v_cvt_pk_bf16_f32 v249, v108, v109
	global_store_dwordx4 v255, v[246:249], s[64:65]
	v_cvt_pk_bf16_f32 v250, v102, v103
	v_cvt_pk_bf16_f32 v251, v104, v105
	v_cvt_pk_bf16_f32 v252, v98, v99
	v_cvt_pk_bf16_f32 v253, v100, v101
	global_store_dwordx4 v255, v[250:253], s[64:65] offset:256
	v_add_u32_e32 v255, 0x20000, v254
	v_cvt_pk_bf16_f32 v246, v94, v95
	v_cvt_pk_bf16_f32 v247, v96, v97
	v_cvt_pk_bf16_f32 v248, v90, v91
	v_cvt_pk_bf16_f32 v249, v92, v93
	global_store_dwordx4 v255, v[246:249], s[64:65]
	v_cvt_pk_bf16_f32 v250, v86, v87
	v_cvt_pk_bf16_f32 v251, v88, v89
	v_cvt_pk_bf16_f32 v252, v82, v83
	v_cvt_pk_bf16_f32 v253, v84, v85
	global_store_dwordx4 v255, v[250:253], s[64:65] offset:256
	v_add_u32_e32 v255, 0x30000, v254
	v_cvt_pk_bf16_f32 v246, v78, v79
	v_cvt_pk_bf16_f32 v247, v80, v81
	v_cvt_pk_bf16_f32 v248, v74, v75
	v_cvt_pk_bf16_f32 v249, v76, v77
	global_store_dwordx4 v255, v[246:249], s[64:65]
	v_cvt_pk_bf16_f32 v250, v70, v71
	v_cvt_pk_bf16_f32 v251, v72, v73
	v_cvt_pk_bf16_f32 v252, v66, v67
	v_cvt_pk_bf16_f32 v253, v68, v69
	global_store_dwordx4 v255, v[250:253], s[64:65] offset:256
	v_add_u32_e32 v255, 0x80000, v254
	v_cvt_pk_bf16_f32 v246, v62, v63
	v_cvt_pk_bf16_f32 v247, v64, v65
	v_cvt_pk_bf16_f32 v248, v58, v59
	v_cvt_pk_bf16_f32 v249, v60, v61
	global_store_dwordx4 v255, v[246:249], s[64:65]
	v_cvt_pk_bf16_f32 v250, v54, v55
	v_cvt_pk_bf16_f32 v251, v56, v57
	v_cvt_pk_bf16_f32 v252, v50, v51
	v_cvt_pk_bf16_f32 v253, v52, v53
	global_store_dwordx4 v255, v[250:253], s[64:65] offset:256
	v_add_u32_e32 v255, 0x90000, v254
	v_cvt_pk_bf16_f32 v246, v46, v47
	v_cvt_pk_bf16_f32 v247, v48, v49
	v_cvt_pk_bf16_f32 v248, v42, v43
	v_cvt_pk_bf16_f32 v249, v44, v45
	global_store_dwordx4 v255, v[246:249], s[64:65]
	v_cvt_pk_bf16_f32 v250, v38, v39
	v_cvt_pk_bf16_f32 v251, v40, v41
	v_cvt_pk_bf16_f32 v252, v34, v35
	v_cvt_pk_bf16_f32 v253, v36, v37
	global_store_dwordx4 v255, v[250:253], s[64:65] offset:256
	v_add_u32_e32 v255, 0xa0000, v254
	v_cvt_pk_bf16_f32 v246, v30, v31
	v_cvt_pk_bf16_f32 v247, v32, v33
	v_cvt_pk_bf16_f32 v248, v26, v27
	v_cvt_pk_bf16_f32 v249, v28, v29
	global_store_dwordx4 v255, v[246:249], s[64:65]
	v_cvt_pk_bf16_f32 v250, v22, v23
	v_cvt_pk_bf16_f32 v251, v24, v25
	v_cvt_pk_bf16_f32 v252, v18, v19
	v_cvt_pk_bf16_f32 v253, v20, v21
	global_store_dwordx4 v255, v[250:253], s[64:65] offset:256
	v_add_u32_e32 v255, 0xb0000, v254
	v_cvt_pk_bf16_f32 v246, v14, v15
	v_cvt_pk_bf16_f32 v247, v16, v17
	v_cvt_pk_bf16_f32 v248, v10, v11
	v_cvt_pk_bf16_f32 v249, v12, v13
	global_store_dwordx4 v255, v[246:249], s[64:65]
	v_cvt_pk_bf16_f32 v250, v6, v7
	v_cvt_pk_bf16_f32 v251, v8, v9
	v_cvt_pk_bf16_f32 v252, v2, v3
	v_cvt_pk_bf16_f32 v253, v4, v5
	global_store_dwordx4 v255, v[250:253], s[64:65] offset:256
	s_branch .LBB0_945
